# FoX fast epilogue, code after it kept at the same addresses as before (padding behind the unit-loop branch)
# speedup vs baseline: 1.0021x; 1.0021x over previous
.LBB0_390:
	v_cmp_gt_u32_e32 vcc, 32, v135
	s_and_saveexec_b64 s[0:1], vcc
	ds_write_b32 v112, v111 offset:49152
	s_or_b64 exec, exec, s[0:1]
	s_waitcnt lgkmcnt(0)
	ds_read_b128 v[160:163], v110 offset:49152
	ds_read_b128 v[164:167], v110 offset:49184
	ds_read_b128 v[168:171], v110 offset:49216
	ds_read_b128 v[172:175], v110 offset:49248
	s_ashr_i32 s29, s28, 31
	s_lshl_b64 s[0:1], s[28:29], 11
	s_add_u32 s0, s30, s0
	s_addc_u32 s1, s31, s1
	s_mov_b32 s98, 0x33333333
	s_mov_b32 s99, 0x33333333
	s_mov_b32 s100, 0xaaaaaaaa
	s_mov_b32 s101, 0xaaaaaaaa
	s_mov_b64 vcc, 0x4000
	v_and_b32_e32 v225, 3, v135
	v_add_u32_e32 v225, v225, v132
	v_and_b32_e32 v226, 28, v134
	v_lshlrev_b32_e32 v225, 11, v225
	v_lshl_add_u32 v216, v226, 1, v225
	v_mov_b32_e32 v217, 0
	v_mov_b32_e32 v225, 0x5040100
	v_mov_b32_e32 v226, 0x3020706
	v_lshl_add_u64 v[216:217], v[216:217], 0, s[0:1]
	v_cndmask_b32_e64 v224, v225, v226, s[100:101]
	v_lshl_add_u64 v[218:219], v[216:217], 0, vcc
	v_lshl_add_u64 v[220:221], v[218:219], 0, vcc
	v_lshl_add_u64 v[222:223], v[220:221], 0, vcc
	s_waitcnt lgkmcnt(0)
	v_rcp_f32_e32 v160, v160
	v_rcp_f32_e32 v161, v161
	v_rcp_f32_e32 v162, v162
	v_rcp_f32_e32 v163, v163
	v_rcp_f32_e32 v164, v164
	v_rcp_f32_e32 v165, v165
	v_rcp_f32_e32 v166, v166
	v_rcp_f32_e32 v167, v167
	v_rcp_f32_e32 v168, v168
	v_rcp_f32_e32 v169, v169
	v_rcp_f32_e32 v170, v170
	v_rcp_f32_e32 v171, v171
	v_rcp_f32_e32 v172, v172
	v_rcp_f32_e32 v173, v173
	v_rcp_f32_e32 v174, v174
	v_rcp_f32_e32 v175, v175
	s_nop 0
	v_mul_f32_e32 v20, v20, v160
	v_mul_f32_e32 v21, v21, v161
	v_mul_f32_e32 v22, v22, v162
	v_mul_f32_e32 v23, v23, v163
	v_mul_f32_e32 v24, v24, v164
	v_mul_f32_e32 v25, v25, v165
	v_mul_f32_e32 v26, v26, v166
	v_mul_f32_e32 v27, v27, v167
	v_mul_f32_e32 v28, v28, v168
	v_mul_f32_e32 v29, v29, v169
	v_mul_f32_e32 v30, v30, v170
	v_mul_f32_e32 v31, v31, v171
	v_mul_f32_e32 v32, v32, v172
	v_mul_f32_e32 v33, v33, v173
	v_mul_f32_e32 v34, v34, v174
	v_mul_f32_e32 v35, v35, v175
	v_cvt_pk_bf16_f32 v20, v20, v21
	v_cvt_pk_bf16_f32 v22, v22, v23
	v_cvt_pk_bf16_f32 v24, v24, v25
	v_cvt_pk_bf16_f32 v26, v26, v27
	v_cvt_pk_bf16_f32 v28, v28, v29
	v_cvt_pk_bf16_f32 v30, v30, v31
	v_cvt_pk_bf16_f32 v32, v32, v33
	v_cvt_pk_bf16_f32 v34, v34, v35
	s_nop 1
	v_mov_b32_dpp v21, v20 quad_perm:[1,0,3,2] row_mask:0xf bank_mask:0xf
	v_mov_b32_dpp v23, v22 quad_perm:[1,0,3,2] row_mask:0xf bank_mask:0xf
	v_mov_b32_dpp v25, v24 quad_perm:[1,0,3,2] row_mask:0xf bank_mask:0xf
	v_mov_b32_dpp v27, v26 quad_perm:[1,0,3,2] row_mask:0xf bank_mask:0xf
	v_mov_b32_dpp v29, v28 quad_perm:[1,0,3,2] row_mask:0xf bank_mask:0xf
	v_mov_b32_dpp v31, v30 quad_perm:[1,0,3,2] row_mask:0xf bank_mask:0xf
	v_mov_b32_dpp v33, v32 quad_perm:[1,0,3,2] row_mask:0xf bank_mask:0xf
	v_mov_b32_dpp v35, v34 quad_perm:[1,0,3,2] row_mask:0xf bank_mask:0xf
	v_perm_b32 v20, v21, v20, v224
	v_perm_b32 v22, v23, v22, v224
	v_perm_b32 v24, v25, v24, v224
	v_perm_b32 v26, v27, v26, v224
	v_perm_b32 v28, v29, v28, v224
	v_perm_b32 v30, v31, v30, v224
	v_perm_b32 v32, v33, v32, v224
	v_perm_b32 v34, v35, v34, v224
	v_cndmask_b32_e64 v21, v20, v22, s[98:99]
	v_cndmask_b32_e64 v25, v24, v26, s[98:99]
	v_cndmask_b32_e64 v29, v28, v30, s[98:99]
	v_cndmask_b32_e64 v33, v32, v34, s[98:99]
	s_nop 1
	v_mov_b32_dpp v23, v21 quad_perm:[2,3,0,1] row_mask:0xf bank_mask:0xf
	v_mov_b32_dpp v27, v25 quad_perm:[2,3,0,1] row_mask:0xf bank_mask:0xf
	v_mov_b32_dpp v31, v29 quad_perm:[2,3,0,1] row_mask:0xf bank_mask:0xf
	v_mov_b32_dpp v35, v33 quad_perm:[2,3,0,1] row_mask:0xf bank_mask:0xf
	v_cndmask_b32_e64 v21, v22, v23, s[98:99]
	v_cndmask_b32_e64 v20, v23, v20, s[98:99]
	v_cndmask_b32_e64 v25, v26, v27, s[98:99]
	v_cndmask_b32_e64 v24, v27, v24, s[98:99]
	v_cndmask_b32_e64 v29, v30, v31, s[98:99]
	v_cndmask_b32_e64 v28, v31, v28, s[98:99]
	v_cndmask_b32_e64 v33, v34, v35, s[98:99]
	v_cndmask_b32_e64 v32, v35, v32, s[98:99]
	global_store_dwordx2 v[216:217], v[20:21], off
	global_store_dwordx2 v[218:219], v[24:25], off
	global_store_dwordx2 v[220:221], v[28:29], off
	global_store_dwordx2 v[222:223], v[32:33], off
	v_mul_f32_e32 v2, v2, v160
	v_mul_f32_e32 v3, v3, v161
	v_mul_f32_e32 v4, v4, v162
	v_mul_f32_e32 v5, v5, v163
	v_mul_f32_e32 v6, v6, v164
	v_mul_f32_e32 v7, v7, v165
	v_mul_f32_e32 v8, v8, v166
	v_mul_f32_e32 v9, v9, v167
	v_mul_f32_e32 v10, v10, v168
	v_mul_f32_e32 v11, v11, v169
	v_mul_f32_e32 v12, v12, v170
	v_mul_f32_e32 v13, v13, v171
	v_mul_f32_e32 v14, v14, v172
	v_mul_f32_e32 v15, v15, v173
	v_mul_f32_e32 v16, v16, v174
	v_mul_f32_e32 v17, v17, v175
	v_cvt_pk_bf16_f32 v2, v2, v3
	v_cvt_pk_bf16_f32 v4, v4, v5
	v_cvt_pk_bf16_f32 v6, v6, v7
	v_cvt_pk_bf16_f32 v8, v8, v9
	v_cvt_pk_bf16_f32 v10, v10, v11
	v_cvt_pk_bf16_f32 v12, v12, v13
	v_cvt_pk_bf16_f32 v14, v14, v15
	v_cvt_pk_bf16_f32 v16, v16, v17
	s_nop 1
	v_mov_b32_dpp v3, v2 quad_perm:[1,0,3,2] row_mask:0xf bank_mask:0xf
	v_mov_b32_dpp v5, v4 quad_perm:[1,0,3,2] row_mask:0xf bank_mask:0xf
	v_mov_b32_dpp v7, v6 quad_perm:[1,0,3,2] row_mask:0xf bank_mask:0xf
	v_mov_b32_dpp v9, v8 quad_perm:[1,0,3,2] row_mask:0xf bank_mask:0xf
	v_mov_b32_dpp v11, v10 quad_perm:[1,0,3,2] row_mask:0xf bank_mask:0xf
	v_mov_b32_dpp v13, v12 quad_perm:[1,0,3,2] row_mask:0xf bank_mask:0xf
	v_mov_b32_dpp v15, v14 quad_perm:[1,0,3,2] row_mask:0xf bank_mask:0xf
	v_mov_b32_dpp v17, v16 quad_perm:[1,0,3,2] row_mask:0xf bank_mask:0xf
	v_perm_b32 v2, v3, v2, v224
	v_perm_b32 v4, v5, v4, v224
	v_perm_b32 v6, v7, v6, v224
	v_perm_b32 v8, v9, v8, v224
	v_perm_b32 v10, v11, v10, v224
	v_perm_b32 v12, v13, v12, v224
	v_perm_b32 v14, v15, v14, v224
	v_perm_b32 v16, v17, v16, v224
	v_cndmask_b32_e64 v3, v2, v4, s[98:99]
	v_cndmask_b32_e64 v7, v6, v8, s[98:99]
	v_cndmask_b32_e64 v11, v10, v12, s[98:99]
	v_cndmask_b32_e64 v15, v14, v16, s[98:99]
	s_nop 1
	v_mov_b32_dpp v5, v3 quad_perm:[2,3,0,1] row_mask:0xf bank_mask:0xf
	v_mov_b32_dpp v9, v7 quad_perm:[2,3,0,1] row_mask:0xf bank_mask:0xf
	v_mov_b32_dpp v13, v11 quad_perm:[2,3,0,1] row_mask:0xf bank_mask:0xf
	v_mov_b32_dpp v17, v15 quad_perm:[2,3,0,1] row_mask:0xf bank_mask:0xf
	v_cndmask_b32_e64 v3, v4, v5, s[98:99]
	v_cndmask_b32_e64 v2, v5, v2, s[98:99]
	v_cndmask_b32_e64 v7, v8, v9, s[98:99]
	v_cndmask_b32_e64 v6, v9, v6, s[98:99]
	v_cndmask_b32_e64 v11, v12, v13, s[98:99]
	v_cndmask_b32_e64 v10, v13, v10, s[98:99]
	v_cndmask_b32_e64 v15, v16, v17, s[98:99]
	v_cndmask_b32_e64 v14, v17, v14, s[98:99]
	global_store_dwordx2 v[216:217], v[2:3], off offset:64
	global_store_dwordx2 v[218:219], v[6:7], off offset:64
	global_store_dwordx2 v[220:221], v[10:11], off offset:64
	global_store_dwordx2 v[222:223], v[14:15], off offset:64
	s_branch .LBB0_324
	s_nop 0
	s_nop 0
	s_nop 0
	s_nop 0
	s_nop 0
	s_nop 0
	s_nop 0
	s_nop 0
	s_nop 0
	s_nop 0
	s_nop 0
	s_nop 0
	s_nop 0
	s_nop 0
	s_nop 0
	s_nop 0
	s_nop 0
	s_nop 0
	s_nop 0
	s_nop 0
	s_nop 0
	s_nop 0
	s_nop 0
	s_nop 0
	s_nop 0
	s_nop 0
	s_nop 0
	s_nop 0
	s_nop 0
	s_nop 0
	s_nop 0
	s_nop 0
	s_nop 0
	s_nop 0
	s_nop 0
	s_nop 0
	s_nop 0
	s_nop 0
	s_nop 0
	s_nop 0
	s_nop 0
	s_nop 0
	s_nop 0
	s_nop 0
	s_nop 0
	s_nop 0
	s_nop 0
	s_nop 0
	s_nop 0
	s_nop 0
	s_nop 0
	s_nop 0
	s_nop 0
	s_nop 0
	s_nop 0
	s_nop 0
	s_nop 0
	s_nop 0
	s_nop 0
	s_nop 0
	s_nop 0
	s_nop 0
	s_nop 0
	s_nop 0
	s_nop 0
	s_nop 0
	s_nop 0
	s_nop 0
	s_nop 0
	s_nop 0
	s_nop 0
	s_nop 0
	s_nop 0
	s_nop 0
	s_nop 0
	s_nop 0
	s_nop 0
	s_nop 0
	s_nop 0
	s_nop 0
	s_nop 0
	s_nop 0
	s_nop 0
	s_nop 0
	s_nop 0
	s_nop 0
	s_nop 0
	s_nop 0
	s_nop 0
	s_nop 0
	s_nop 0
	s_nop 0
	s_nop 0
	s_nop 0
	s_nop 0
	s_nop 0
	s_nop 0
	s_nop 0
	s_nop 0
	s_nop 0
	s_nop 0
	s_nop 0
	s_nop 0
	s_nop 0
	s_nop 0
	s_nop 0
	s_nop 0
	s_nop 0
	s_nop 0
	s_nop 0
	s_nop 0
	s_nop 0
	s_nop 0
	s_nop 0
	s_nop 0
	s_nop 0
	s_nop 0
	s_nop 0
	s_nop 0
	s_nop 0
	s_nop 0
	s_nop 0
	s_nop 0
	s_nop 0
	s_nop 0
	s_nop 0
	s_nop 0
	s_nop 0
	s_nop 0
	s_nop 0
	s_nop 0
	s_nop 0
	s_nop 0
	s_nop 0
	s_nop 0
	s_nop 0
	s_nop 0
	s_nop 0
	s_nop 0
	s_nop 0
	s_nop 0
	s_nop 0
	s_nop 0
	s_nop 0
	s_nop 0
	s_nop 0
	s_nop 0
	s_nop 0
	s_nop 0
	s_nop 0
	s_nop 0
	s_nop 0
	s_nop 0
	s_nop 0
	s_nop 0
	s_nop 0
	s_nop 0
	s_nop 0
	s_nop 0
	s_nop 0
	s_nop 0
	s_nop 0
	s_nop 0
	s_nop 0
	s_nop 0
	s_nop 0
	s_nop 0
	s_nop 0
	s_nop 0
	s_nop 0
	s_nop 0
	s_nop 0
	s_nop 0
	s_nop 0
	s_nop 0
	s_nop 0
	s_nop 0
	s_nop 0
	s_nop 0
	s_nop 0
	s_nop 0
	s_nop 0
	s_nop 0
	s_nop 0
	s_nop 0
	s_nop 0
	s_nop 0
	s_nop 0
	s_nop 0
	s_nop 0
	s_nop 0
	s_nop 0
	s_nop 0
	s_nop 0
	s_nop 0
	s_nop 0
	s_nop 0
	s_nop 0
	s_nop 0
	s_nop 0
	s_nop 0
	s_nop 0
	s_nop 0
	s_nop 0
	s_nop 0
	s_nop 0
	s_nop 0
	s_nop 0
	s_nop 0
	s_nop 0
	s_nop 0
	s_nop 0
	s_nop 0
	s_nop 0
	s_nop 0
	s_nop 0
	s_nop 0
	s_nop 0
	s_nop 0
	s_nop 0
	s_nop 0
	s_nop 0
	s_nop 0
	s_nop 0
	s_nop 0
	s_nop 0
	s_nop 0
	s_nop 0
	s_nop 0
	s_nop 0
	s_nop 0
	s_nop 0
	s_nop 0
	s_nop 0
	s_nop 0
	s_nop 0
	s_nop 0
	s_nop 0
	s_nop 0
	s_nop 0
	s_nop 0
	s_nop 0
	s_nop 0
	s_nop 0
	s_nop 0
	s_nop 0
	s_nop 0
	s_nop 0
	s_nop 0
	s_nop 0
	s_nop 0
	s_nop 0
	s_nop 0
	s_nop 0
	s_nop 0
	s_nop 0
	s_nop 0
	s_nop 0
	s_nop 0
	s_nop 0
	s_nop 0
	s_nop 0
	s_nop 0
	s_nop 0
	s_nop 0
	s_nop 0
	s_nop 0
	s_nop 0
	s_nop 0
	s_nop 0
	s_nop 0
	s_nop 0
	s_nop 0
	s_nop 0
	s_nop 0
	s_nop 0
	s_nop 0
	s_nop 0
	s_nop 0
	s_nop 0
	s_nop 0
	s_nop 0
	s_nop 0
	s_nop 0
	s_nop 0
	s_nop 0
	s_nop 0
	s_nop 0
	s_nop 0
	s_nop 0
	s_nop 0
	s_nop 0
	s_nop 0
	s_nop 0
	s_nop 0
	s_nop 0
	s_nop 0
	s_nop 0
	s_nop 0
	s_nop 0
	s_nop 0
	s_nop 0
	s_nop 0
	s_nop 0
	s_nop 0
	s_nop 0
	s_nop 0
	s_nop 0
	s_nop 0
	s_nop 0
	s_nop 0
	s_nop 0
	s_nop 0
	s_nop 0
	s_nop 0
	s_nop 0
	s_nop 0
	s_nop 0
	s_nop 0
	s_nop 0
	s_nop 0
	s_nop 0
	s_nop 0
	s_nop 0
	s_nop 0
	s_nop 0
	s_nop 0
	s_nop 0
	s_nop 0
	s_nop 0
	s_nop 0
	s_nop 0
	s_nop 0
	s_nop 0
	s_nop 0
	s_nop 0
	s_nop 0
	s_nop 0
	s_nop 0
	s_nop 0
	s_nop 0
	s_nop 0
	s_nop 0
	s_nop 0
	s_nop 0
	s_nop 0
	s_nop 0
	s_nop 0
	s_nop 0
	s_nop 0
	s_nop 0
	s_nop 0
	s_nop 0
	s_nop 0
	s_nop 0
	s_nop 0
	s_nop 0
